# P4 out-proj epilogue software-pipelined: 16 x-loads in flight with counted vmcnt instead of 32 serialized load-wait-add-store round trips
# speedup vs baseline: 1.0044x; 1.0044x over previous
;     __device__ __forceinline__ void operator()(const pg8::f32x4 (&acc)[2][2][4][2], const pg8::Unit& u, int wr, int wc, int fr, int fq) const {
;         const int row0 = u.pm * 256 + wr * 64 + fr, col0 = u.pn * 256 + wc * 32 + 4 * fq;
; #pragma unroll
;         for (int ai = 0; ai < 2; ++ai)
; #pragma unroll
;             for (int m = 0; m < 4; ++m) { const size_t off = (size_t)(row0 + ai * 128 + m * 16) * DM + col0;
; #pragma unroll
;                 for (int bj = 0; bj < 2; ++bj)
; #pragma unroll
;                     for (int n = 0; n < 2; ++n) { const size_t o2 = off + bj * 128 + n * 16; *(pg8::f32x4*)(out + o2) = *(const pg8::f32x4*)(x + o2) + acc[ai][bj][m][n]; }
;                 if (m & 1) asm volatile("" ::: "memory"); }
;     }
.LBB0_481:
	v_lshl_add_u32 v146, s26, 8, v136
	v_lshl_or_b32 v148, s55, 8, v138
	v_ashrrev_i32_e32 v147, 31, v146
	v_ashrrev_i32_e32 v149, 31, v148
	v_lshlrev_b64 v[134:135], 10, v[146:147]
	v_lshl_add_u64 v[134:135], v[134:135], 0, v[148:149]
	v_lshlrev_b64 v[134:135], 2, v[134:135]
	s_andn2_b64 vcc, exec, s[20:21]
	s_mov_b64 s[20:21], -1
	v_add_u32_e32 v219, 0x10000, v134
	v_add_u32_e32 v220, 0x20000, v134
	v_add_u32_e32 v221, 0x30000, v134
	v_add_u32_e32 v222, 0x80000, v134
	v_add_u32_e32 v223, 0x90000, v134
	v_add_u32_e32 v224, 0xa0000, v134
	v_add_u32_e32 v225, 0xb0000, v134
	global_load_dwordx4 v[142:145], v134, s[36:37]
	global_load_dwordx4 v[146:149], v134, s[36:37] offset:64
	global_load_dwordx4 v[156:159], v134, s[36:37] offset:512
	global_load_dwordx4 v[160:163], v134, s[36:37] offset:576
	global_load_dwordx4 v[164:167], v219, s[36:37]
	global_load_dwordx4 v[168:171], v219, s[36:37] offset:64
	global_load_dwordx4 v[172:175], v219, s[36:37] offset:512
	global_load_dwordx4 v[176:179], v219, s[36:37] offset:576
	global_load_dwordx4 v[180:183], v220, s[36:37]
	global_load_dwordx4 v[184:187], v220, s[36:37] offset:64
	global_load_dwordx4 v[188:191], v220, s[36:37] offset:512
	global_load_dwordx4 v[192:195], v220, s[36:37] offset:576
	global_load_dwordx4 v[196:199], v221, s[36:37]
	global_load_dwordx4 v[200:203], v221, s[36:37] offset:64
	global_load_dwordx4 v[204:207], v221, s[36:37] offset:512
	global_load_dwordx4 v[208:211], v221, s[36:37] offset:576
	s_waitcnt vmcnt(15)
	v_pk_add_f32 v[124:125], v[124:125], v[142:143]
	v_pk_add_f32 v[126:127], v[126:127], v[144:145]
	global_store_dwordx4 v134, v[124:127], s[50:51]
	global_load_dwordx4 v[142:145], v222, s[36:37]
	s_waitcnt vmcnt(16)
	v_pk_add_f32 v[120:121], v[120:121], v[146:147]
	v_pk_add_f32 v[122:123], v[122:123], v[148:149]
	global_store_dwordx4 v134, v[120:123], s[50:51] offset:64
	global_load_dwordx4 v[146:149], v222, s[36:37] offset:64
	s_waitcnt vmcnt(17)
	v_pk_add_f32 v[116:117], v[116:117], v[156:157]
	v_pk_add_f32 v[118:119], v[118:119], v[158:159]
	global_store_dwordx4 v134, v[116:119], s[50:51] offset:512
	global_load_dwordx4 v[156:159], v222, s[36:37] offset:512
	s_waitcnt vmcnt(18)
	v_pk_add_f32 v[104:105], v[104:105], v[160:161]
	v_pk_add_f32 v[106:107], v[106:107], v[162:163]
	global_store_dwordx4 v134, v[104:107], s[50:51] offset:576
	global_load_dwordx4 v[160:163], v222, s[36:37] offset:576
	s_waitcnt vmcnt(19)
	v_pk_add_f32 v[112:113], v[112:113], v[164:165]
	v_pk_add_f32 v[114:115], v[114:115], v[166:167]
	global_store_dwordx4 v219, v[112:115], s[50:51]
	global_load_dwordx4 v[164:167], v223, s[36:37]
	s_waitcnt vmcnt(20)
	v_pk_add_f32 v[108:109], v[108:109], v[168:169]
	v_pk_add_f32 v[110:111], v[110:111], v[170:171]
	global_store_dwordx4 v219, v[108:111], s[50:51] offset:64
	global_load_dwordx4 v[168:171], v223, s[36:37] offset:64
	s_waitcnt vmcnt(21)
	v_pk_add_f32 v[100:101], v[100:101], v[172:173]
	v_pk_add_f32 v[102:103], v[102:103], v[174:175]
	global_store_dwordx4 v219, v[100:103], s[50:51] offset:512
	global_load_dwordx4 v[172:175], v223, s[36:37] offset:512
	s_waitcnt vmcnt(22)
	v_pk_add_f32 v[88:89], v[88:89], v[176:177]
	v_pk_add_f32 v[90:91], v[90:91], v[178:179]
	global_store_dwordx4 v219, v[88:91], s[50:51] offset:576
	global_load_dwordx4 v[176:179], v223, s[36:37] offset:576
	s_waitcnt vmcnt(23)
	v_pk_add_f32 v[96:97], v[96:97], v[180:181]
	v_pk_add_f32 v[98:99], v[98:99], v[182:183]
	global_store_dwordx4 v220, v[96:99], s[50:51]
	global_load_dwordx4 v[180:183], v224, s[36:37]
	s_waitcnt vmcnt(24)
	v_pk_add_f32 v[92:93], v[92:93], v[184:185]
	v_pk_add_f32 v[94:95], v[94:95], v[186:187]
	global_store_dwordx4 v220, v[92:95], s[50:51] offset:64
	global_load_dwordx4 v[184:187], v224, s[36:37] offset:64
	s_waitcnt vmcnt(25)
	v_pk_add_f32 v[84:85], v[84:85], v[188:189]
	v_pk_add_f32 v[86:87], v[86:87], v[190:191]
	global_store_dwordx4 v220, v[84:87], s[50:51] offset:512
	global_load_dwordx4 v[188:191], v224, s[36:37] offset:512
	s_waitcnt vmcnt(26)
; #define PG8_BAR __builtin_amdgcn_s_barrier()
; template <class Epi, class Sched, bool ALIGN_EPI = false, bool SP2 = false>
; __device__ __forceinline__ void gemm_phase(PG8_LAS unsigned char* lds, const Gemm g, const Sched& S, const Epi& E) {
;     ...
;         if constexpr (ALIGN_EPI) { if (wr == 1) PG8_BAR; }
;     __device__ __forceinline__ void operator()(const pg8::f32x4 (&acc)[2][2][4][2], const pg8::Unit& u, int wr, int wc, int fr, int fq) const {
;     ...
;             for (int m = 0; m < 4; ++m) { const size_t off = (size_t)(row0 + ai * 128 + m * 16) * DM + col0;
; #pragma unroll
;                 for (int bj = 0; bj < 2; ++bj)
; #pragma unroll
;                     for (int n = 0; n < 2; ++n) { const size_t o2 = off + bj * 128 + n * 16; *(pg8::f32x4*)(out + o2) = *(const pg8::f32x4*)(x + o2) + acc[ai][bj][m][n]; }
;                 if (m & 1) asm volatile("" ::: "memory"); }
	v_pk_add_f32 v[72:73], v[72:73], v[192:193]
	v_pk_add_f32 v[74:75], v[74:75], v[194:195]
	global_store_dwordx4 v220, v[72:75], s[50:51] offset:576
	global_load_dwordx4 v[192:195], v224, s[36:37] offset:576
	s_waitcnt vmcnt(27)
	v_pk_add_f32 v[80:81], v[80:81], v[196:197]
	v_pk_add_f32 v[82:83], v[82:83], v[198:199]
	global_store_dwordx4 v221, v[80:83], s[50:51]
	global_load_dwordx4 v[196:199], v225, s[36:37]
	s_waitcnt vmcnt(28)
	v_pk_add_f32 v[76:77], v[76:77], v[200:201]
	v_pk_add_f32 v[78:79], v[78:79], v[202:203]
	global_store_dwordx4 v221, v[76:79], s[50:51] offset:64
	global_load_dwordx4 v[200:203], v225, s[36:37] offset:64
	s_waitcnt vmcnt(29)
	v_pk_add_f32 v[68:69], v[68:69], v[204:205]
	v_pk_add_f32 v[70:71], v[70:71], v[206:207]
	global_store_dwordx4 v221, v[68:71], s[50:51] offset:512
	global_load_dwordx4 v[204:207], v225, s[36:37] offset:512
	s_waitcnt vmcnt(30)
	v_pk_add_f32 v[64:65], v[64:65], v[208:209]
	v_pk_add_f32 v[66:67], v[66:67], v[210:211]
	global_store_dwordx4 v221, v[64:67], s[50:51] offset:576
	global_load_dwordx4 v[208:211], v225, s[36:37] offset:576
	s_waitcnt vmcnt(30)
	v_pk_add_f32 v[60:61], v[60:61], v[142:143]
	v_pk_add_f32 v[62:63], v[62:63], v[144:145]
	global_store_dwordx4 v222, v[60:63], s[50:51]
	s_waitcnt vmcnt(29)
	v_pk_add_f32 v[56:57], v[56:57], v[146:147]
	v_pk_add_f32 v[58:59], v[58:59], v[148:149]
	global_store_dwordx4 v222, v[56:59], s[50:51] offset:64
	s_waitcnt vmcnt(28)
	v_pk_add_f32 v[52:53], v[52:53], v[156:157]
	v_pk_add_f32 v[54:55], v[54:55], v[158:159]
	global_store_dwordx4 v222, v[52:55], s[50:51] offset:512
	s_waitcnt vmcnt(27)
	v_pk_add_f32 v[40:41], v[40:41], v[160:161]
	v_pk_add_f32 v[42:43], v[42:43], v[162:163]
	global_store_dwordx4 v222, v[40:43], s[50:51] offset:576
	s_waitcnt vmcnt(26)
	v_pk_add_f32 v[48:49], v[48:49], v[164:165]
	v_pk_add_f32 v[50:51], v[50:51], v[166:167]
	global_store_dwordx4 v223, v[48:51], s[50:51]
	s_waitcnt vmcnt(25)
	v_pk_add_f32 v[44:45], v[44:45], v[168:169]
	v_pk_add_f32 v[46:47], v[46:47], v[170:171]
	global_store_dwordx4 v223, v[44:47], s[50:51] offset:64
	s_waitcnt vmcnt(24)
	v_pk_add_f32 v[36:37], v[36:37], v[172:173]
	v_pk_add_f32 v[38:39], v[38:39], v[174:175]
	global_store_dwordx4 v223, v[36:39], s[50:51] offset:512
	s_waitcnt vmcnt(23)
	v_pk_add_f32 v[24:25], v[24:25], v[176:177]
	v_pk_add_f32 v[26:27], v[26:27], v[178:179]
	global_store_dwordx4 v223, v[24:27], s[50:51] offset:576
	s_waitcnt vmcnt(22)
	v_pk_add_f32 v[32:33], v[32:33], v[180:181]
	v_pk_add_f32 v[34:35], v[34:35], v[182:183]
	global_store_dwordx4 v224, v[32:35], s[50:51]
	s_waitcnt vmcnt(21)
	v_pk_add_f32 v[28:29], v[28:29], v[184:185]
	v_pk_add_f32 v[30:31], v[30:31], v[186:187]
	global_store_dwordx4 v224, v[28:31], s[50:51] offset:64
	s_waitcnt vmcnt(20)
	v_pk_add_f32 v[20:21], v[20:21], v[188:189]
	v_pk_add_f32 v[22:23], v[22:23], v[190:191]
	global_store_dwordx4 v224, v[20:23], s[50:51] offset:512
	s_waitcnt vmcnt(19)
	v_pk_add_f32 v[8:9], v[8:9], v[192:193]
	v_pk_add_f32 v[10:11], v[10:11], v[194:195]
	global_store_dwordx4 v224, v[8:11], s[50:51] offset:576
	s_waitcnt vmcnt(18)
	v_pk_add_f32 v[16:17], v[16:17], v[196:197]
	v_pk_add_f32 v[18:19], v[18:19], v[198:199]
	global_store_dwordx4 v225, v[16:19], s[50:51]
	s_waitcnt vmcnt(17)
	v_pk_add_f32 v[12:13], v[12:13], v[200:201]
	v_pk_add_f32 v[14:15], v[14:15], v[202:203]
	global_store_dwordx4 v225, v[12:15], s[50:51] offset:64
	s_waitcnt vmcnt(16)
	v_pk_add_f32 v[4:5], v[4:5], v[204:205]
	v_pk_add_f32 v[6:7], v[6:7], v[206:207]
	global_store_dwordx4 v225, v[4:7], s[50:51] offset:512
	s_waitcnt vmcnt(15)
	v_pk_add_f32 v[0:1], v[0:1], v[208:209]
	v_pk_add_f32 v[2:3], v[2:3], v[210:211]
	global_store_dwordx4 v225, v[0:3], s[50:51] offset:576
	s_cbranch_vccnz .LBB0_469
	s_andn2_b64 vcc, exec, s[0:1]
	s_cbranch_vccnz .LBB0_468
	s_barrier
	s_branch .LBB0_468
